# fill_tabs for SwiGLU GEMM phases rewritten by hand: per-wave units, all 17 loads of a unit in flight instead of 12 serialized iterations
# baseline (speedup 1.0000x reference)
; #define LAS __attribute__((address_space(3)))
; __device__ __forceinline__ int opaque_tid() { int t = threadIdx.x; asm volatile("" : "+v"(t)); return t; }
; template <int MODE, class Sched> __device__ __forceinline__ void fill_tabs(LAS unsigned char* lds, const Sched& S, const float* rsq, const float* v0, const float* v1) {
;     const int tid = opaque_tid(); LAS float* tab = (LAS float*)(lds + RSTD_OFF); LAS float* vec = (LAS float*)(lds + VEC_OFF);
;     for (int i = 0; i < 12; ++i) { pg8::Unit u; if (!S.next(i, u)) break;
;         const int s = u.pm < 128 ? (u.pm >> 5) : 4;
;         if (MODE != 2) {
;             if (tid < 256) { const float* p = rsq + ((size_t)u.pm * 256 + tid) * 16; float t = 0.f;
; #pragma unroll
;                 for (int j = 0; j < 4; ++j) { const f32x4 v = *(const f32x4*)(p + 4 * j); t += (v.x + v.y) + (v.z + v.w); }
;                 tab[i * 256 + tid] = rsqrtf(t * (1.0f / 1024.0f) + EPS); }
;             else { const int t = tid - 256;
;                 vec[i * 256 + t] = MODE == 1 ? v0[s * 13312 + (t < 128 ? u.pn * 128 + t : 2816 + u.pn * 128 + (t - 128))] : v0[s * 13312 + u.pn * 256 + t]; }
; __global__ void __launch_bounds__(512) fwd_mega(Params P) {
;     ...
;         if (st == 0 || st == 6) {
;             EpiSwiglu E; E.rtab = (const LAS float*)(lds + RSTD_OFF); E.vtab = (const LAS float*)(lds + VEC_OFF); E.hid = HID;
;             const float* sWp = SW + (size_t)l * 5 * 13312 + (st == 0 ? 0 : 7680);
;             pg8::Gemm g{AP, (const bf16_t*)(WL + (st == 0 ? LW_WIN1 : LW_WIN2)), MT, 5632, 1024};
;             pg8::Order2 S; S.init(22, (st == 6 && lastl) ? 0 : 22, G, c);
;             fill_tabs<1>(lds, S, RSQ, sWp, nullptr);
.LBB0_718:
	s_and_b64 vcc, exec, s[0:1]
	s_cbranch_vccz .LBB0_751
	s_cmp_eq_u32 s59, 6
	v_readlane_b32 s7, v244, 41
	s_cselect_b64 s[8:9], -1, 0
	s_cmp_eq_u32 s59, 0
	s_mul_hi_u32 s6, s7, 0x41000
	s_mul_i32 s7, s7, 0x41000
	v_readlane_b32 s12, v246, 44
	s_cselect_b64 s[0:1], -1, 0
	s_add_u32 s12, s12, s7
	v_readlane_b32 s7, v246, 45
	s_addc_u32 s13, s7, s6
	s_and_b64 s[6:7], s[0:1], exec
	s_cselect_b32 s6, 0, 0x7800
	s_add_u32 s6, s12, s6
	s_addc_u32 s7, s13, 0
	v_readlane_b32 s12, v244, 39
	v_readlane_b32 s13, v244, 40
	s_and_b64 s[8:9], s[8:9], s[12:13]
	s_and_b64 s[8:9], s[8:9], exec
	s_movk_i32 s8, 0xb58
	s_cselect_b32 s78, 0xb00, s8
	s_waitcnt vmcnt(0)
	v_mov_b32_e32 v4, v218
	v_readlane_b32 s8, v244, 20
	s_mov_b32 s3, 0
	v_add_u32_e32 v6, 0xffffff00, v4
	s_waitcnt lgkmcnt(1)
	v_lshl_add_u32 v2, v4, 2, s8
	s_movk_i32 s8, 0xff
	v_cmp_lt_i32_e64 s[38:39], s8, v4
	v_readlane_b32 s8, v244, 21
	v_ashrrev_i32_e32 v5, 31, v4
	v_add_u32_e32 v7, 0x980, v4
	s_waitcnt lgkmcnt(0)
	v_lshl_add_u32 v3, v6, 2, s8
	s_movk_i32 s8, 0x180
	v_lshlrev_b64 v[0:1], 6, v[4:5]
	v_cmp_gt_u32_e32 vcc, s8, v4
	v_lshl_add_u64 v[0:1], s[76:77], 0, v[0:1]
	s_mov_b64 s[14:15], s[72:73]
	v_cndmask_b32_e32 v4, v7, v6, vcc
	v_and_b32_e32 v2, 63, v218
	v_lshrrev_b32_e32 v3, 6, v218
	v_lshlrev_b32_e32 v8, 8, v2
	v_mov_b32_e32 v9, 0
	v_readfirstlane_b32 s3, v3
	v_lshlrev_b32_e32 v5, 4, v2
	v_cmp_lt_u32_e32 vcc, 31, v2
	v_mov_b32_e32 v10, 0x2a00
	s_nop 1
	v_cndmask_b32_e32 v10, 0, v10, vcc
	v_add_u32_e32 v10, v10, v5
	v_mov_b32_e32 v11, 0
.Lft1_pass:
	s_cmp_gt_u32 s3, 11
	s_cbranch_scc1 .Lft1_done
	s_mul_i32 s8, s3, s4
	s_add_u32 s14, s72, s8
	s_cmp_ge_u32 s14, s78
	s_cbranch_scc1 .Lft1_done
	s_cmp_lt_u32 s14, 0xb00
	s_cbranch_scc1 .Lft1_lat
	s_add_i32 s8, s14, 0xfffff500
	s_mul_hi_i32 s9, s8, 0x2e8ba2e9
	s_lshr_b32 s12, s9, 31
	s_ashr_i32 s9, s9, 2
	s_add_i32 s9, s9, s12
	s_add_i32 s18, s9, 0x80
	s_mul_i32 s9, s9, 22
	s_sub_i32 s8, s8, s9
	s_branch .Lft1_dec

; template <int MODE, class Sched> __device__ __forceinline__ void fill_tabs(LAS unsigned char* lds, const Sched& S, const float* rsq, const float* v0, const float* v1) {
;     ...
;     for (int i = 0; i < 12; ++i) { pg8::Unit u; if (!S.next(i, u)) break;
;         const int s = u.pm < 128 ? (u.pm >> 5) : 4;
;         if (MODE != 2) {
;             if (tid < 256) { const float* p = rsq + ((size_t)u.pm * 256 + tid) * 16; float t = 0.f;
; #pragma unroll
;                 for (int j = 0; j < 4; ++j) { const f32x4 v = *(const f32x4*)(p + 4 * j); t += (v.x + v.y) + (v.z + v.w); }
;                 tab[i * 256 + tid] = rsqrtf(t * (1.0f / 1024.0f) + EPS); }
;             else { const int t = tid - 256;
;                 vec[i * 256 + t] = MODE == 1 ? v0[s * 13312 + (t < 128 ? u.pn * 128 + t : 2816 + u.pn * 128 + (t - 128))] : v0[s * 13312 + u.pn * 256 + t]; }
.Lft1_dec:
	s_lshl_b32 s12, s18, 14
	s_add_u32 s12, s76, s12
	s_addc_u32 s13, s77, 0
	v_lshl_add_u64 v[0:1], s[12:13], 0, v[8:9]
	global_load_dwordx4 v[24:27], v[0:1], off
	global_load_dwordx4 v[28:31], v[0:1], off offset:16
	global_load_dwordx4 v[32:35], v[0:1], off offset:32
	global_load_dwordx4 v[36:39], v[0:1], off offset:48
	global_load_dwordx4 v[40:43], v[0:1], off offset:64
	global_load_dwordx4 v[44:47], v[0:1], off offset:80
	global_load_dwordx4 v[48:51], v[0:1], off offset:96
	global_load_dwordx4 v[52:55], v[0:1], off offset:112
	global_load_dwordx4 v[56:59], v[0:1], off offset:128
	global_load_dwordx4 v[60:63], v[0:1], off offset:144
	global_load_dwordx4 v[64:67], v[0:1], off offset:160
	global_load_dwordx4 v[68:71], v[0:1], off offset:176
	global_load_dwordx4 v[72:75], v[0:1], off offset:192
	global_load_dwordx4 v[76:79], v[0:1], off offset:208
	global_load_dwordx4 v[80:83], v[0:1], off offset:224
	global_load_dwordx4 v[84:87], v[0:1], off offset:240
	s_min_i32 s9, s18, 0x80
	s_lshr_b32 s9, s9, 5
	s_mulk_i32 s9, 0x3400
	s_lshl_b32 s8, s8, 7
	s_add_i32 s9, s9, s8
	s_lshl_b32 s9, s9, 2
	s_add_u32 s12, s6, s9
	s_addc_u32 s13, s7, 0
	v_lshl_add_u64 v[12:13], s[12:13], 0, v[10:11]
	global_load_dwordx4 v[88:91], v[12:13], off
	s_lshl_b32 s9, s3, 10
	v_add_u32_e32 v14, s9, v5
	v_add_u32_e32 v15, 0x20010, v14
	v_add_u32_e32 v16, 0x23010, v14
	s_waitcnt vmcnt(0)
	v_add_f32_e32 v24, v24, v25
	v_add_f32_e32 v26, v26, v27
	v_add_f32_e32 v28, v28, v29
	v_add_f32_e32 v30, v30, v31
	v_add_f32_e32 v32, v32, v33
	v_add_f32_e32 v34, v34, v35
	v_add_f32_e32 v36, v36, v37
	v_add_f32_e32 v38, v38, v39
	v_add_f32_e32 v24, v24, v26
	v_add_f32_e32 v28, v28, v30
	v_add_f32_e32 v32, v32, v34
	v_add_f32_e32 v36, v36, v38
	v_add_f32_e32 v92, v24, v28
	v_add_f32_e32 v92, v92, v32
	v_add_f32_e32 v92, v92, v36
	v_fmamk_f32 v92, v92, 0x3a800000, v223
	v_add_f32_e32 v40, v40, v41
	v_add_f32_e32 v42, v42, v43
	v_add_f32_e32 v44, v44, v45
	v_add_f32_e32 v46, v46, v47
	v_add_f32_e32 v48, v48, v49
	v_add_f32_e32 v50, v50, v51
	v_add_f32_e32 v52, v52, v53
	v_add_f32_e32 v54, v54, v55
	v_add_f32_e32 v40, v40, v42
	v_add_f32_e32 v44, v44, v46
	v_add_f32_e32 v48, v48, v50
	v_add_f32_e32 v52, v52, v54
	v_add_f32_e32 v93, v40, v44
	v_add_f32_e32 v93, v93, v48
	v_add_f32_e32 v93, v93, v52
	v_fmamk_f32 v93, v93, 0x3a800000, v223
	v_add_f32_e32 v56, v56, v57
	v_add_f32_e32 v58, v58, v59
	v_add_f32_e32 v60, v60, v61
	v_add_f32_e32 v62, v62, v63
	v_add_f32_e32 v64, v64, v65
	v_add_f32_e32 v66, v66, v67
	v_add_f32_e32 v68, v68, v69
	v_add_f32_e32 v70, v70, v71
	v_add_f32_e32 v56, v56, v58
	v_add_f32_e32 v60, v60, v62
	v_add_f32_e32 v64, v64, v66
	v_add_f32_e32 v68, v68, v70
	v_add_f32_e32 v94, v56, v60
	v_add_f32_e32 v94, v94, v64
	v_add_f32_e32 v94, v94, v68
	v_fmamk_f32 v94, v94, 0x3a800000, v223
	v_add_f32_e32 v72, v72, v73
	v_add_f32_e32 v74, v74, v75
	v_add_f32_e32 v76, v76, v77
	v_add_f32_e32 v78, v78, v79
	v_add_f32_e32 v80, v80, v81
	v_add_f32_e32 v82, v82, v83
	v_add_f32_e32 v84, v84, v85
	v_add_f32_e32 v86, v86, v87
	v_add_f32_e32 v72, v72, v74
	v_add_f32_e32 v76, v76, v78
	v_add_f32_e32 v80, v80, v82
	v_add_f32_e32 v84, v84, v86
	v_add_f32_e32 v95, v72, v76
	v_add_f32_e32 v95, v95, v80
	v_add_f32_e32 v95, v95, v84
	v_fmamk_f32 v95, v95, 0x3a800000, v223
	v_rsq_f32_e32 v92, v92
	v_rsq_f32_e32 v93, v93
	v_rsq_f32_e32 v94, v94
	v_rsq_f32_e32 v95, v95
	s_nop 1
	ds_write_b128 v15, v[92:95]
	ds_write_b128 v16, v[88:91]
	s_add_i32 s3, s3, 8
	s_branch .Lft1_pass
; __device__ __forceinline__ int opaque_tid() { int t = threadIdx.x; asm volatile("" : "+v"(t)); return t; }
; #define PG8_STAGE(bufoff, gbase, voff) do { _Pragma("unroll") for (int _i = 0; _i < 2; ++_i) \
;         __builtin_amdgcn_global_load_lds((const unsigned*)((const char*)(gbase) + (voff)[_i]), (LAS unsigned*)(lds + (bufoff) + ldsw + _i * 8192), 16, 0, 0); } while (0)
; #define PG8_WAIT_V(n) asm volatile("s_waitcnt vmcnt(" #n ")" ::: "memory")
; #define PG8_BAR __builtin_amdgcn_s_barrier()
; template <class Epi, class Sched>
; __device__ __forceinline__ void gemm_phase(LAS unsigned char* lds, const Gemm g, const Sched& S, const Epi& E) {
;     const int tid = opaque_tid(), wid = __builtin_amdgcn_readfirstlane(tid >> 6), lane = tid & 63, wr = wid >> 2, wc = wid & 3, fr = lane & 15, fq = lane >> 4;
;     const int K = g.K, ntf = K / BK, nts = S.ks > 1 ? ntf / S.ks : ntf;
;     unsigned voffA[2], voffB[2];
; #pragma unroll
;     for (int i = 0; i < 2; ++i) { int R, C; stage_rc(tid * 16 + i * 8192, R, C); const int Rb = Epi::PERM ? ((R & ~31) + perm32(R & 31)) : R;
;         voffA[i] = (unsigned)(R * K + C) * 2u; voffB[i] = (unsigned)(Rb * K + C) * 2u; }
;     const size_t kstep = (size_t)(BK * 2);
;     const size_t hstep = (size_t)HALF * K * 2;
;     const size_t tstep = 2 * hstep;
;     const unsigned ldsw = (unsigned)wid * 1024u;
;     const int aoff = lds_byte(wr * 64 + fr, fq * 8), boff = lds_byte(wc * 32 + fr, fq * 8);
;     ...
;     Unit cur, nxt; int ui = 0;
;     if (!S.next(0, cur)) return;
;     f32x4 acc[2][2][4][2];
; #pragma unroll
;     for (int a = 0; a < 2; ++a)
; #pragma unroll
;         for (int b = 0; b < 2; ++b)
; #pragma unroll
;             for (int m = 0; m < 4; ++m)
; #pragma unroll
;                 for (int n = 0; n < 2; ++n) acc[a][b][m][n] = (f32x4){0.f, 0.f, 0.f, 0.f};
;     bf16x8 At[4][2], B0[2][2], B1[2][2];
;     const char* cA = (const char*)g.A + (size_t)cur.pm * tstep + (cur.kc > 0 ? (size_t)cur.kc * nts * kstep : 0); const char* cB = (const char*)g.Bt + (size_t)cur.pn * tstep + (cur.kc > 0 ? (size_t)cur.kc * nts * kstep : 0);
;     S.a_ready(cur);
;     PG8_STAGE(PG8_SB(0, 0), cB, voffB); PG8_STAGE(PG8_SB(0, 1), cB + hstep, voffB); PG8_STAGE(PG8_SA(0, 0), cA, voffA); PG8_STAGE(PG8_SA(0, 1), cA + hstep, voffA);
;     if (wr == 1) PG8_BAR;
;     PG8_WAIT_V(2); PG8_BAR;
.Lft1_done:
.LBB0_731:
	v_mov_b32_e32 v5, v218
	s_waitcnt lgkmcnt(0)
	s_barrier
	s_cmp_ge_i32 s72, s78
	v_readfirstlane_b32 s6, v5
	s_cbranch_scc1 .LBB0_751
	v_lshlrev_b32_e32 v0, 4, v5
	v_add_u32_e32 v1, 0x2000, v0
	v_ashrrev_i32_e32 v2, 31, v1
	v_lshrrev_b32_e32 v2, 22, v2
	v_add_u32_e32 v2, v1, v2
	v_ashrrev_i32_e32 v4, 10, v2
	v_mul_i32_i24_e32 v2, 0x400, v4
	v_sub_u32_e32 v1, v1, v2
	v_lshrrev_b32_e32 v2, 4, v1
	v_bitop3_b32 v1, v2, v1, 32 bitop3:0x6c
	s_ashr_i32 s7, s6, 6
	v_ashrrev_i32_e32 v2, 31, v1
	s_ashr_i32 s3, s6, 8
	s_lshl_b32 s8, s7, 10
	v_lshrrev_b32_e32 v2, 26, v2
	s_and_b64 s[0:1], s[0:1], exec
	v_add_u32_e32 v2, v1, v2
	v_lshlrev_b32_e32 v3, 3, v4
	s_cselect_b32 s0, 0, 0x1680000
	v_readlane_b32 s1, v244, 42
	v_ashrrev_i32_e32 v6, 6, v2
	v_and_b32_e32 v3, -16, v3
	s_add_u32 s9, s1, s0
	v_readlane_b32 s0, v244, 43
	v_add_u32_e32 v3, v6, v3
	s_addc_u32 s12, s0, 0
	v_and_b32_e32 v7, 3, v6
	s_mov_b32 s0, 0x1fffe0
	v_lshrrev_b32_e32 v8, 2, v3
	v_lshlrev_b32_e32 v9, 1, v3
	v_and_b32_e32 v2, 0xc0, v2
	v_and_or_b32 v7, v3, s0, v7
	v_and_b32_e32 v8, 4, v8
	v_and_b32_e32 v9, 24, v9
	v_sub_u32_e32 v1, v1, v2
	v_or3_b32 v8, v7, v8, v9
	v_lshlrev_b32_e32 v7, 5, v4
	v_ashrrev_i16_sdwa v1, v224, sext(v1) dst_sel:DWORD dst_unused:UNUSED_PAD src0_sel:DWORD src1_sel:BYTE_0
	v_and_b32_e32 v9, 32, v7
	v_bfe_i32 v7, v1, 0, 16
	v_add_lshl_u32 v1, v9, v7, 1
	v_lshl_add_u32 v144, v8, 11, v1
	v_lshl_add_u32 v146, v3, 11, v1
	v_bfe_i32 v1, v5, 27, 1
	v_lshrrev_b32_e32 v1, 22, v1
	v_add_u32_e32 v1, v0, v1
	v_and_b32_e32 v1, 0xfffffc00, v1
	v_sub_u32_e32 v0, v0, v1
	v_lshrrev_b32_e32 v1, 4, v0
	v_bitop3_b32 v1, v1, v0, 32 bitop3:0x6c
	v_ashrrev_i32_e32 v0, 31, v0
	v_lshrrev_b32_e32 v0, 26, v0
	v_add_u32_e32 v0, v1, v0
	v_ashrrev_i32_e32 v8, 6, v0
	v_ashrrev_i32_e32 v0, 31, v5
	v_lshrrev_b32_e32 v0, 26, v0
	v_add_u32_e32 v0, v5, v0
	v_ashrrev_i32_e32 v9, 6, v0
	v_lshlrev_b32_e32 v0, 3, v9
	v_and_b32_e32 v0, -16, v0
	v_add_u32_e32 v0, v8, v0
	v_and_b32_e32 v2, 3, v8
	v_lshrrev_b32_e32 v3, 2, v0
	v_lshlrev_b32_e32 v10, 1, v0
	v_and_or_b32 v2, v0, s0, v2
	v_and_b32_e32 v3, 4, v3
	v_and_b32_e32 v10, 24, v10
	v_or3_b32 v2, v2, v3, v10
	v_mul_i32_i24_e32 v10, 64, v8
	v_sub_u32_e32 v1, v1, v10
	v_lshlrev_b32_e32 v3, 5, v9
	v_ashrrev_i16_sdwa v1, v224, sext(v1) dst_sel:DWORD dst_unused:UNUSED_PAD src0_sel:DWORD src1_sel:BYTE_0
	v_readlane_b32 s0, v244, 0
	v_and_b32_e32 v3, 32, v3
	v_bfe_i32 v10, v1, 0, 16
	v_readlane_b32 s1, v244, 1
	s_add_u32 s24, s9, s0
	v_add_lshl_u32 v1, v3, v10, 1
	s_addc_u32 s25, s12, s1
	s_add_i32 s28, s8, 0
	v_lshl_add_u32 v184, v2, 11, v1
	s_add_i32 m0, s28, 0x10000
	v_lshl_add_u32 v148, v0, 11, v1
	global_load_lds_dwordx4 v184, s[24:25]
	s_add_i32 m0, s28, 0x12000
	s_add_u32 s0, s24, 0x40000
	global_load_lds_dwordx4 v144, s[24:25]
	s_addc_u32 s1, s25, 0
	s_add_i32 m0, s28, 0x14000
	s_add_i32 s29, s28, 0x2000
	global_load_lds_dwordx4 v184, s[0:1]
	s_add_i32 m0, s28, 0x16000
	s_add_i32 s30, s28, 0x4000
	global_load_lds_dwordx4 v144, s[0:1]
	v_readlane_b32 s0, v244, 2
	s_mov_b32 m0, s28
	v_readlane_b32 s1, v244, 3
	s_add_i32 s31, s28, 0x6000
	v_mov_b32_e32 v145, v185
	s_cmp_eq_u32 s3, 1
	v_lshl_add_u64 v[0:1], s[24:25], 0, v[184:185]
	v_lshl_add_u64 v[2:3], s[24:25], 0, v[144:145]
	global_load_lds_dwordx4 v148, s[0:1]
	s_mov_b32 m0, s29
	s_nop 0
	global_load_lds_dwordx4 v146, s[0:1]
	v_readlane_b32 s0, v244, 4
	s_mov_b32 m0, s30
	v_readlane_b32 s1, v244, 5
	s_nop 4
	global_load_lds_dwordx4 v148, s[0:1]
	s_mov_b32 m0, s31
	s_nop 0
	global_load_lds_dwordx4 v146, s[0:1]
	s_cselect_b64 s[0:1], -1, 0
	s_cmp_lg_u32 s3, 1
	s_cbranch_scc1 .LBB0_734
	s_barrier
